# W_q^T stored chunk-swizzled; P6 K-loop replaced by 4-slot paired-DMA pipelined loop that issues its own prologue and reads B through the map
# speedup vs baseline: 1.0157x; 1.0157x over previous
.Ltr_p_d4:
	s_lshr_b32 s6, s5, 5
	s_and_b32 s7, s5, 31
	s_mov_b32 s12, 0x2000
	s_movk_i32 s13, 31
	s_mul_i32 s8, s6, 0x80000
	s_lshl_b32 s9, s7, 8
	s_add_u32 s8, s8, s9
	s_add_u32 s10, s38, s8
	s_addc_u32 s11, s39, 0
	s_lshl_b32 s8, s7, 18
	s_add_u32 s8, s8, 0x19288000
	s_add_u32 s14, s94, s8
	s_addc_u32 s15, s95, 0

.LBB0_787:
	v_add_u32_e32 v0, v76, v77
	v_cmp_lt_i32_e32 vcc, s47, v0
	s_cbranch_vccnz .LBB0_786
	v_readfirstlane_b32 s38, v0
	s_ashr_i32 s39, s38, 31
	s_lshr_b32 s39, s39, 25
	s_add_i32 s39, s38, s39
	s_ashr_i32 s44, s39, 7
	s_lshl_b32 s40, s44, 3
	s_and_b32 s39, s39, 0xffffff80
	s_sub_i32 s41, 0x44, s40
	s_cmpk_gt_i32 s38, 0x3ff
	s_cselect_b32 s41, s41, 8
	s_abs_i32 s38, s41
	v_cvt_f32_u32_e32 v1, s38
	v_subrev_u32_e32 v0, s39, v0
	s_sub_i32 s39, 0, s38
	v_sub_u32_e32 v2, 0, v0
	v_rcp_iflag_f32_e32 v1, v1
	v_max_i32_e32 v2, v0, v2
	v_xor_b32_e32 v3, s41, v0
	v_ashrrev_i32_e32 v3, 31, v3
	v_mul_f32_e32 v1, 0x4f7ffffe, v1
	v_cvt_u32_f32_e32 v1, v1
	v_mov_b32_e32 v8, v204
	v_add_u32_e32 v0, s40, v0
	v_mul_lo_u32 v4, s39, v1
	v_mul_hi_u32 v4, v1, v4
	v_add_u32_e32 v1, v1, v4
	v_mul_hi_u32 v1, v2, v1
	v_mul_lo_u32 v4, v1, s38
	v_sub_u32_e32 v2, v2, v4
	v_add_u32_e32 v4, 1, v1
	v_subrev_u32_e32 v5, s38, v2
	v_cmp_le_u32_e32 vcc, s38, v2
	s_mulk_i32 s44, 0x78
	v_and_b32_e32 v9, 31, v8
	v_cndmask_b32_e32 v1, v1, v4, vcc
	v_cndmask_b32_e32 v2, v2, v5, vcc
	v_add_u32_e32 v4, 1, v1
	v_cmp_le_u32_e32 vcc, s38, v2
	v_bfe_u32 v2, v8, 4, 2
	v_bitop3_b32 v2, v2, v8, 3 bitop3:0x78
	v_cndmask_b32_e32 v1, v1, v4, vcc
	v_xor_b32_e32 v1, v1, v3
	v_sub_u32_e32 v1, v1, v3
	v_ashrrev_i32_e32 v3, 6, v8
	v_readfirstlane_b32 s38, v1
	v_lshlrev_b32_e32 v5, 9, v8
	s_mul_i32 s45, s41, s38
	s_ashr_i32 s39, s38, 31
	v_lshlrev_b32_e32 v2, 3, v2
	v_lshlrev_b32_e32 v4, 16, v3
	v_and_b32_e32 v5, 0x7800, v5
	v_subrev_u32_e32 v0, s45, v0
	s_lshl_b64 s[40:41], s[38:39], 19
	v_or3_b32 v2, v5, v4, v2
	v_ashrrev_i32_e32 v1, 31, v0
	s_add_u32 s42, s48, s40
	v_lshl_add_u32 v64, v3, 11, 32
	v_ashrrev_i32_e32 v3, 31, v2
	v_lshlrev_b64 v[66:67], 18, v[0:1]
	v_lshlrev_b64 v[0:1], 19, v[0:1]
	s_addc_u32 s43, s49, s41
	v_lshlrev_b64 v[2:3], 1, v[2:3]
	v_lshl_add_u64 v[0:1], s[6:7], 0, v[0:1]
	v_lshl_add_u64 v[4:5], s[42:43], 0, v[2:3]
	v_readfirstlane_b32 s42, v64
	v_add_u32_e32 v11, 0x400, v64
	v_add_u32_e32 v10, 0x2000, v64
	v_lshl_add_u64 v[0:1], v[0:1], 0, v[2:3]
	s_mov_b32 m0, s42
	v_readfirstlane_b32 s42, v11
	v_lshl_add_u64 v[6:7], v[0:1], 0, s[10:11]
	s_mov_b32 m0, s42
	v_readfirstlane_b32 s42, v10
	v_add_u32_e32 v10, 0x2400, v64
	s_mov_b32 m0, s42
	v_readfirstlane_b32 s42, v10
	v_add_u32_e32 v10, 0x4000, v64
	v_lshl_add_u64 v[6:7], v[4:5], 0, s[10:11]
	s_mov_b32 m0, s42
	v_readfirstlane_b32 s42, v10
	v_add_u32_e32 v10, 0x4400, v64
	v_lshl_add_u64 v[6:7], v[0:1], 0, 64
	s_mov_b32 m0, s42
	v_readfirstlane_b32 s42, v10
	v_add_u32_e32 v10, 0x6000, v64
	v_lshl_add_u64 v[6:7], v[0:1], 0, s[12:13]
	s_mov_b32 m0, s42
	v_readfirstlane_b32 s42, v10
	v_add_u32_e32 v10, 0x6400, v64
	v_lshl_add_u64 v[6:7], v[4:5], 0, 64
	s_mov_b32 m0, s42
	v_readfirstlane_b32 s42, v10
	v_add_u32_e32 v10, 0x8000, v64
	v_lshl_add_u64 v[6:7], v[4:5], 0, s[12:13]
	s_mov_b32 m0, s42
	v_readfirstlane_b32 s42, v10
	v_lshl_add_u64 v[6:7], v[0:1], 0, s[14:15]
	s_mov_b32 m0, s42
	v_lshl_add_u64 v[0:1], v[0:1], 0, s[16:17]
	v_add_u32_e32 v6, 0x8400, v64
	s_add_u32 s40, s94, s40
	v_readfirstlane_b32 s42, v6
	v_add_u32_e32 v6, 0xa000, v64
	s_mov_b32 m0, s42
	v_readfirstlane_b32 s42, v6
	v_lshl_add_u64 v[0:1], v[4:5], 0, s[14:15]
	s_mov_b32 m0, s42
	s_addc_u32 s41, s95, s41
	v_lshl_add_u64 v[0:1], v[4:5], 0, s[16:17]
	v_add_u32_e32 v4, 0xa400, v64
	v_lshrrev_b32_e32 v5, 1, v8
	v_readfirstlane_b32 s42, v4
	s_mov_b32 m0, s42
	v_bfe_u32 v4, v8, 2, 2
	v_bfe_u32 v0, v8, 5, 1
	v_lshrrev_b32_e32 v1, 2, v8
	v_bitop3_b32 v1, v0, v1, 3 bitop3:0x78
	v_bitop3_b32 v0, v0, v4, 2 bitop3:0x36
	v_lshlrev_b32_e32 v82, 4, v0
	v_subrev_u32_e32 v0, s45, v78
	v_subrev_u32_e32 v0, s44, v0
	v_lshlrev_b32_e32 v81, 4, v1
	v_ashrrev_i32_e32 v1, 31, v0
	v_lshlrev_b64 v[0:1], 19, v[0:1]
	v_and_or_b32 v5, v5, s52, v9
	v_lshl_add_u64 v[0:1], s[94:95], 0, v[0:1]
	v_lshlrev_b32_e32 v79, 6, v5
	v_lshlrev_b32_e32 v5, 6, v8
	v_lshl_add_u64 v[70:71], v[0:1], 0, v[2:3]
	v_mov_b32_e32 v0, 0
	s_mov_b32 s54, 0
	s_mov_b32 s53, 1
	v_and_b32_e32 v80, 0x17c0, v5
	v_lshl_add_u64 v[68:69], s[40:41], 0, v[2:3]
	s_mov_b64 s[40:41], 0
	v_mov_b32_e32 v1, v0
	v_mov_b32_e32 v2, v0
	v_mov_b32_e32 v3, v0
	v_mov_b32_e32 v4, v0
	v_mov_b32_e32 v5, v0
	v_mov_b32_e32 v6, v0
	v_mov_b32_e32 v7, v0
	v_mov_b32_e32 v8, v0
	v_mov_b32_e32 v9, v0
	v_mov_b32_e32 v10, v0
	v_mov_b32_e32 v11, v0
	v_mov_b32_e32 v12, v0
	v_mov_b32_e32 v13, v0
	v_mov_b32_e32 v14, v0
	v_mov_b32_e32 v15, v0
	v_mov_b32_e32 v16, v0
	v_mov_b32_e32 v17, v0
	v_mov_b32_e32 v18, v0
	v_mov_b32_e32 v19, v0
	v_mov_b32_e32 v20, v0
	v_mov_b32_e32 v21, v0
	v_mov_b32_e32 v22, v0
	v_mov_b32_e32 v23, v0
	v_mov_b32_e32 v24, v0
	v_mov_b32_e32 v25, v0
	v_mov_b32_e32 v26, v0
	v_mov_b32_e32 v27, v0
	v_mov_b32_e32 v28, v0
	v_mov_b32_e32 v29, v0
	v_mov_b32_e32 v30, v0
	v_mov_b32_e32 v31, v0
	v_mov_b32_e32 v32, v0
	v_mov_b32_e32 v33, v0
	v_mov_b32_e32 v34, v0
	v_mov_b32_e32 v35, v0
	v_mov_b32_e32 v36, v0
	v_mov_b32_e32 v37, v0
	v_mov_b32_e32 v38, v0
	v_mov_b32_e32 v39, v0
	v_mov_b32_e32 v40, v0
	v_mov_b32_e32 v41, v0
	v_mov_b32_e32 v42, v0
	v_mov_b32_e32 v43, v0
	v_mov_b32_e32 v44, v0
	v_mov_b32_e32 v45, v0
	v_mov_b32_e32 v46, v0
	v_mov_b32_e32 v47, v0
	v_mov_b32_e32 v48, v0
	v_mov_b32_e32 v49, v0
	v_mov_b32_e32 v50, v0
	v_mov_b32_e32 v51, v0
	v_mov_b32_e32 v52, v0
	v_mov_b32_e32 v53, v0
	v_mov_b32_e32 v54, v0
	v_mov_b32_e32 v55, v0
	v_mov_b32_e32 v56, v0
	v_mov_b32_e32 v57, v0
	v_mov_b32_e32 v58, v0
	v_mov_b32_e32 v59, v0
	v_mov_b32_e32 v60, v0
	v_mov_b32_e32 v61, v0
	v_mov_b32_e32 v62, v0
	v_mov_b32_e32 v63, v0
	v_add3_u32 v140, v79, v81, 32
	v_add3_u32 v141, v79, v82, 32
	v_add_u32_e32 v142, 0x2020, v80
	v_add_u32_e32 v143, v142, v82
	v_add_u32_e32 v142, v142, v81
	v_subrev_u32_e32 v144, s94, v70
	v_subrev_u32_e32 v146, s94, v68
	v_add_u32_e32 v144, 0x13288000, v144
	v_add_u32_e32 v146, 0x19288000, v146
	v_add_u32_e32 v145, 0x10000, v144
	v_add_u32_e32 v147, 0x10000, v146
	v_readfirstlane_b32 s64, v64
	s_nop 0
	s_add_u32 s65, s64, 0x2000
	s_mov_b64 s[60:61], s[94:95]
	s_add_u32 s62, s94, 64
	s_addc_u32 s63, s95, 0
	v_bfe_u32 v148, v204, 2, 4
	v_lshlrev_b32_e32 v148, 7, v148
	s_mov_b32 s70, 0
	s_movk_i32 s71, 0x800
	v_xad_u32 v149, s70, v148, v146
	v_xad_u32 v150, s71, v148, v147
	s_add_u32 m0, s64, 0x0
	s_nop 0
	global_load_lds_dwordx4 v144, s[60:61]
	s_add_u32 m0, s64, 0x4000
	s_nop 0
	global_load_lds_dwordx4 v144, s[62:63]
	s_add_u32 m0, s64, 0x400
	s_nop 0
	global_load_lds_dwordx4 v145, s[60:61]
	s_add_u32 m0, s64, 0x4400
	s_nop 0
	global_load_lds_dwordx4 v145, s[62:63]
	s_add_u32 m0, s65, 0x0
	s_nop 0
	global_load_lds_dwordx4 v149, s[94:95]
	s_add_u32 m0, s65, 0x3fc0
	s_nop 0
	global_load_lds_dwordx4 v149, s[94:95] offset:64
	s_add_u32 m0, s65, 0x400
	s_nop 0
	global_load_lds_dwordx4 v150, s[94:95]
	s_add_u32 m0, s65, 0x43c0
	s_nop 0
	global_load_lds_dwordx4 v150, s[94:95] offset:64
	s_add_u32 s70, s70, 0x80
	s_xor_b32 s71, s70, 0x800
	s_add_u32 s60, s60, 128
	s_addc_u32 s61, s61, 0
	s_add_u32 s62, s62, 128
	s_addc_u32 s63, s63, 0
	v_xad_u32 v149, s70, v148, v146
	v_xad_u32 v150, s71, v148, v147
	s_add_u32 m0, s64, 0x8000
	s_nop 0
	global_load_lds_dwordx4 v144, s[60:61]
	s_add_u32 m0, s64, 0xc000
	s_nop 0
	global_load_lds_dwordx4 v144, s[62:63]
	s_add_u32 m0, s64, 0x8400
	s_nop 0
	global_load_lds_dwordx4 v145, s[60:61]
	s_add_u32 m0, s64, 0xc400
	s_nop 0
	global_load_lds_dwordx4 v145, s[62:63]
	s_add_u32 m0, s65, 0x8000
	s_nop 0
	global_load_lds_dwordx4 v149, s[94:95]
	s_add_u32 m0, s65, 0xbfc0
	s_nop 0
	global_load_lds_dwordx4 v149, s[94:95] offset:64
	s_add_u32 m0, s65, 0x8400
	s_nop 0
	global_load_lds_dwordx4 v150, s[94:95]
	s_add_u32 m0, s65, 0xc3c0
	s_nop 0
	global_load_lds_dwordx4 v150, s[94:95] offset:64
	s_add_u32 s70, s70, 0x80
	s_xor_b32 s71, s70, 0x800
	s_add_u32 s60, s60, 128
	s_addc_u32 s61, s61, 0
	s_add_u32 s62, s62, 128
	s_addc_u32 s63, s63, 0
	s_waitcnt vmcnt(9)
	s_barrier
	ds_read_b128 v[108:111], v142 offset:0
	ds_read_b128 v[112:115], v142 offset:2048
	ds_read_b128 v[116:119], v140 offset:0
	ds_read_b128 v[120:123], v140 offset:2048
	s_waitcnt lgkmcnt(0)
	s_setprio 1
	v_mfma_f32_32x32x16_bf16 v[48:63], v[116:119], v[108:111], v[48:63]
	v_mfma_f32_32x32x16_bf16 v[32:47], v[116:119], v[112:115], v[32:47]
	v_mfma_f32_32x32x16_bf16 v[16:31], v[120:123], v[108:111], v[16:31]
	v_mfma_f32_32x32x16_bf16 v[0:15], v[120:123], v[112:115], v[0:15]
	s_setprio 0
	ds_read_b128 v[124:127], v143 offset:0
	ds_read_b128 v[128:131], v143 offset:2048
	ds_read_b128 v[132:135], v141 offset:0
	ds_read_b128 v[136:139], v141 offset:2048
	s_waitcnt vmcnt(8) lgkmcnt(0)
	s_barrier
	ds_read_b128 v[108:111], v142 offset:16384
	ds_read_b128 v[112:115], v142 offset:18432
	ds_read_b128 v[116:119], v140 offset:16384
	ds_read_b128 v[120:123], v140 offset:18432
	s_setprio 1
	v_mfma_f32_32x32x16_bf16 v[48:63], v[132:135], v[124:127], v[48:63]
	v_mfma_f32_32x32x16_bf16 v[32:47], v[132:135], v[128:131], v[32:47]
	v_mfma_f32_32x32x16_bf16 v[16:31], v[136:139], v[124:127], v[16:31]
	v_mfma_f32_32x32x16_bf16 v[0:15], v[136:139], v[128:131], v[0:15]
	s_setprio 0
	s_waitcnt lgkmcnt(0)
	s_setprio 1
	v_mfma_f32_32x32x16_bf16 v[48:63], v[116:119], v[108:111], v[48:63]
	v_mfma_f32_32x32x16_bf16 v[32:47], v[116:119], v[112:115], v[32:47]
	v_mfma_f32_32x32x16_bf16 v[16:31], v[120:123], v[108:111], v[16:31]
	v_mfma_f32_32x32x16_bf16 v[0:15], v[120:123], v[112:115], v[0:15]
	s_setprio 0
	ds_read_b128 v[124:127], v143 offset:16384
	ds_read_b128 v[128:131], v143 offset:18432
	ds_read_b128 v[132:135], v141 offset:16384
	ds_read_b128 v[136:139], v141 offset:18432
	s_waitcnt vmcnt(1) lgkmcnt(0)
	s_barrier
	ds_read_b128 v[108:111], v142 offset:32768
	ds_read_b128 v[112:115], v142 offset:34816
	ds_read_b128 v[116:119], v140 offset:32768
	ds_read_b128 v[120:123], v140 offset:34816
	s_setprio 1
	v_mfma_f32_32x32x16_bf16 v[48:63], v[132:135], v[124:127], v[48:63]
	v_mfma_f32_32x32x16_bf16 v[32:47], v[132:135], v[128:131], v[32:47]
	v_mfma_f32_32x32x16_bf16 v[16:31], v[136:139], v[124:127], v[16:31]
	v_mfma_f32_32x32x16_bf16 v[0:15], v[136:139], v[128:131], v[0:15]
	s_setprio 0
	s_add_u32 m0, s64, 0x0
	s_nop 0
	global_load_lds_dwordx4 v144, s[60:61]
	s_add_u32 m0, s64, 0x4000
	s_nop 0
	global_load_lds_dwordx4 v144, s[62:63]
	s_add_u32 m0, s64, 0x400
	s_nop 0
	global_load_lds_dwordx4 v145, s[60:61]
	s_add_u32 m0, s64, 0x4400
	s_nop 0
	global_load_lds_dwordx4 v145, s[62:63]
	s_waitcnt lgkmcnt(0)
	s_setprio 1
	v_mfma_f32_32x32x16_bf16 v[48:63], v[116:119], v[108:111], v[48:63]
	v_mfma_f32_32x32x16_bf16 v[32:47], v[116:119], v[112:115], v[32:47]
	v_mfma_f32_32x32x16_bf16 v[16:31], v[120:123], v[108:111], v[16:31]
	v_mfma_f32_32x32x16_bf16 v[0:15], v[120:123], v[112:115], v[0:15]
	s_setprio 0
	ds_read_b128 v[124:127], v143 offset:32768
	ds_read_b128 v[128:131], v143 offset:34816
	ds_read_b128 v[132:135], v141 offset:32768
	ds_read_b128 v[136:139], v141 offset:34816
	v_xad_u32 v149, s70, v148, v146
	v_xad_u32 v150, s71, v148, v147
	s_add_u32 m0, s65, 0x0
	s_nop 0
	global_load_lds_dwordx4 v149, s[94:95]
	s_add_u32 m0, s65, 0x3fc0
	s_nop 0
	global_load_lds_dwordx4 v149, s[94:95] offset:64
	s_add_u32 m0, s65, 0x400
	s_nop 0
	global_load_lds_dwordx4 v150, s[94:95]
	s_add_u32 m0, s65, 0x43c0
	s_nop 0
	global_load_lds_dwordx4 v150, s[94:95] offset:64
	s_add_u32 s70, s70, 0x80
	s_xor_b32 s71, s70, 0x800
	s_add_u32 s60, s60, 128
	s_addc_u32 s61, s61, 0
	s_add_u32 s62, s62, 128
	s_addc_u32 s63, s63, 0
	s_waitcnt vmcnt(8) lgkmcnt(0)
	s_barrier
	ds_read_b128 v[108:111], v142 offset:49152
	ds_read_b128 v[112:115], v142 offset:51200
	ds_read_b128 v[116:119], v140 offset:49152
	ds_read_b128 v[120:123], v140 offset:51200
	s_setprio 1
	v_mfma_f32_32x32x16_bf16 v[48:63], v[132:135], v[124:127], v[48:63]
	v_mfma_f32_32x32x16_bf16 v[32:47], v[132:135], v[128:131], v[32:47]
	v_mfma_f32_32x32x16_bf16 v[16:31], v[136:139], v[124:127], v[16:31]
	v_mfma_f32_32x32x16_bf16 v[0:15], v[136:139], v[128:131], v[0:15]
	s_setprio 0
	s_waitcnt lgkmcnt(0)
	s_setprio 1
	v_mfma_f32_32x32x16_bf16 v[48:63], v[116:119], v[108:111], v[48:63]
	v_mfma_f32_32x32x16_bf16 v[32:47], v[116:119], v[112:115], v[32:47]
	v_mfma_f32_32x32x16_bf16 v[16:31], v[120:123], v[108:111], v[16:31]
	v_mfma_f32_32x32x16_bf16 v[0:15], v[120:123], v[112:115], v[0:15]
	s_setprio 0
	ds_read_b128 v[124:127], v143 offset:49152
	ds_read_b128 v[128:131], v143 offset:51200
	ds_read_b128 v[132:135], v141 offset:49152
	ds_read_b128 v[136:139], v141 offset:51200
	s_mov_b32 s69, 14
.Lp6_kloop:
	s_waitcnt vmcnt(0) lgkmcnt(0)
	s_barrier
	ds_read_b128 v[108:111], v142 offset:0
	ds_read_b128 v[112:115], v142 offset:2048
	ds_read_b128 v[116:119], v140 offset:0
	ds_read_b128 v[120:123], v140 offset:2048
	s_setprio 1
	v_mfma_f32_32x32x16_bf16 v[48:63], v[132:135], v[124:127], v[48:63]
	v_mfma_f32_32x32x16_bf16 v[32:47], v[132:135], v[128:131], v[32:47]
	v_mfma_f32_32x32x16_bf16 v[16:31], v[136:139], v[124:127], v[16:31]
	v_mfma_f32_32x32x16_bf16 v[0:15], v[136:139], v[128:131], v[0:15]
	s_setprio 0
	s_add_u32 m0, s64, 0x8000
	s_nop 0
	global_load_lds_dwordx4 v144, s[60:61]
	s_add_u32 m0, s64, 0xc000
	s_nop 0
	global_load_lds_dwordx4 v144, s[62:63]
	s_add_u32 m0, s64, 0x8400
	s_nop 0
	global_load_lds_dwordx4 v145, s[60:61]
	s_add_u32 m0, s64, 0xc400
	s_nop 0
	global_load_lds_dwordx4 v145, s[62:63]
	s_waitcnt lgkmcnt(0)
	s_setprio 1
	v_mfma_f32_32x32x16_bf16 v[48:63], v[116:119], v[108:111], v[48:63]
	v_mfma_f32_32x32x16_bf16 v[32:47], v[116:119], v[112:115], v[32:47]
	v_mfma_f32_32x32x16_bf16 v[16:31], v[120:123], v[108:111], v[16:31]
	v_mfma_f32_32x32x16_bf16 v[0:15], v[120:123], v[112:115], v[0:15]
	s_setprio 0
	ds_read_b128 v[124:127], v143 offset:0
	ds_read_b128 v[128:131], v143 offset:2048
	ds_read_b128 v[132:135], v141 offset:0
	ds_read_b128 v[136:139], v141 offset:2048
	v_xad_u32 v149, s70, v148, v146
	v_xad_u32 v150, s71, v148, v147
	s_add_u32 m0, s65, 0x8000
	s_nop 0
	global_load_lds_dwordx4 v149, s[94:95]
	s_add_u32 m0, s65, 0xbfc0
	s_nop 0
	global_load_lds_dwordx4 v149, s[94:95] offset:64
	s_add_u32 m0, s65, 0x8400
	s_nop 0
	global_load_lds_dwordx4 v150, s[94:95]
	s_add_u32 m0, s65, 0xc3c0
	s_nop 0
	global_load_lds_dwordx4 v150, s[94:95] offset:64
	s_add_u32 s70, s70, 0x80
	s_xor_b32 s71, s70, 0x800
	s_add_u32 s60, s60, 128
	s_addc_u32 s61, s61, 0
	s_add_u32 s62, s62, 128
	s_addc_u32 s63, s63, 0
	s_waitcnt lgkmcnt(0)
	s_barrier
	ds_read_b128 v[108:111], v142 offset:16384
	ds_read_b128 v[112:115], v142 offset:18432
	ds_read_b128 v[116:119], v140 offset:16384
	ds_read_b128 v[120:123], v140 offset:18432
	s_setprio 1
	v_mfma_f32_32x32x16_bf16 v[48:63], v[132:135], v[124:127], v[48:63]
	v_mfma_f32_32x32x16_bf16 v[32:47], v[132:135], v[128:131], v[32:47]
	v_mfma_f32_32x32x16_bf16 v[16:31], v[136:139], v[124:127], v[16:31]
	v_mfma_f32_32x32x16_bf16 v[0:15], v[136:139], v[128:131], v[0:15]
	s_setprio 0
	s_waitcnt lgkmcnt(0)
	s_setprio 1
	v_mfma_f32_32x32x16_bf16 v[48:63], v[116:119], v[108:111], v[48:63]
	v_mfma_f32_32x32x16_bf16 v[32:47], v[116:119], v[112:115], v[32:47]
	v_mfma_f32_32x32x16_bf16 v[16:31], v[120:123], v[108:111], v[16:31]
	v_mfma_f32_32x32x16_bf16 v[0:15], v[120:123], v[112:115], v[0:15]
	s_setprio 0
	ds_read_b128 v[124:127], v143 offset:16384
	ds_read_b128 v[128:131], v143 offset:18432
	ds_read_b128 v[132:135], v141 offset:16384
	ds_read_b128 v[136:139], v141 offset:18432
	s_waitcnt vmcnt(0) lgkmcnt(0)
	s_barrier
	ds_read_b128 v[108:111], v142 offset:32768
	ds_read_b128 v[112:115], v142 offset:34816
	ds_read_b128 v[116:119], v140 offset:32768
	ds_read_b128 v[120:123], v140 offset:34816
	s_setprio 1
	v_mfma_f32_32x32x16_bf16 v[48:63], v[132:135], v[124:127], v[48:63]
	v_mfma_f32_32x32x16_bf16 v[32:47], v[132:135], v[128:131], v[32:47]
	v_mfma_f32_32x32x16_bf16 v[16:31], v[136:139], v[124:127], v[16:31]
	v_mfma_f32_32x32x16_bf16 v[0:15], v[136:139], v[128:131], v[0:15]
	s_setprio 0
	s_add_u32 m0, s64, 0x0
	s_nop 0
	global_load_lds_dwordx4 v144, s[60:61]
	s_add_u32 m0, s64, 0x4000
	s_nop 0
	global_load_lds_dwordx4 v144, s[62:63]
	s_add_u32 m0, s64, 0x400
	s_nop 0
	global_load_lds_dwordx4 v145, s[60:61]
	s_add_u32 m0, s64, 0x4400
	s_nop 0
	global_load_lds_dwordx4 v145, s[62:63]
	s_waitcnt lgkmcnt(0)
	s_setprio 1
	v_mfma_f32_32x32x16_bf16 v[48:63], v[116:119], v[108:111], v[48:63]
	v_mfma_f32_32x32x16_bf16 v[32:47], v[116:119], v[112:115], v[32:47]
	v_mfma_f32_32x32x16_bf16 v[16:31], v[120:123], v[108:111], v[16:31]
	v_mfma_f32_32x32x16_bf16 v[0:15], v[120:123], v[112:115], v[0:15]
	s_setprio 0
	ds_read_b128 v[124:127], v143 offset:32768
	ds_read_b128 v[128:131], v143 offset:34816
	ds_read_b128 v[132:135], v141 offset:32768
	ds_read_b128 v[136:139], v141 offset:34816
	v_xad_u32 v149, s70, v148, v146
	v_xad_u32 v150, s71, v148, v147
	s_add_u32 m0, s65, 0x0
	s_nop 0
	global_load_lds_dwordx4 v149, s[94:95]
	s_add_u32 m0, s65, 0x3fc0
	s_nop 0
	global_load_lds_dwordx4 v149, s[94:95] offset:64
	s_add_u32 m0, s65, 0x400
	s_nop 0
	global_load_lds_dwordx4 v150, s[94:95]
	s_add_u32 m0, s65, 0x43c0
	s_nop 0
	global_load_lds_dwordx4 v150, s[94:95] offset:64
	s_add_u32 s70, s70, 0x80
	s_xor_b32 s71, s70, 0x800
	s_add_u32 s60, s60, 128
	s_addc_u32 s61, s61, 0
	s_add_u32 s62, s62, 128
	s_addc_u32 s63, s63, 0
	s_waitcnt lgkmcnt(0)
	s_barrier
	ds_read_b128 v[108:111], v142 offset:49152
	ds_read_b128 v[112:115], v142 offset:51200
	ds_read_b128 v[116:119], v140 offset:49152
	ds_read_b128 v[120:123], v140 offset:51200
	s_setprio 1
	v_mfma_f32_32x32x16_bf16 v[48:63], v[132:135], v[124:127], v[48:63]
	v_mfma_f32_32x32x16_bf16 v[32:47], v[132:135], v[128:131], v[32:47]
	v_mfma_f32_32x32x16_bf16 v[16:31], v[136:139], v[124:127], v[16:31]
	v_mfma_f32_32x32x16_bf16 v[0:15], v[136:139], v[128:131], v[0:15]
	s_setprio 0
	s_waitcnt lgkmcnt(0)
	s_setprio 1
	v_mfma_f32_32x32x16_bf16 v[48:63], v[116:119], v[108:111], v[48:63]
	v_mfma_f32_32x32x16_bf16 v[32:47], v[116:119], v[112:115], v[32:47]
	v_mfma_f32_32x32x16_bf16 v[16:31], v[120:123], v[108:111], v[16:31]
	v_mfma_f32_32x32x16_bf16 v[0:15], v[120:123], v[112:115], v[0:15]
	s_setprio 0
	ds_read_b128 v[124:127], v143 offset:49152
	ds_read_b128 v[128:131], v143 offset:51200
	ds_read_b128 v[132:135], v141 offset:49152
	ds_read_b128 v[136:139], v141 offset:51200
	s_sub_u32 s69, s69, 1
	s_cmp_lg_u32 s69, 0
	s_cbranch_scc1 .Lp6_kloop
	s_waitcnt vmcnt(0) lgkmcnt(0)
	s_barrier
	ds_read_b128 v[108:111], v142 offset:0
	ds_read_b128 v[112:115], v142 offset:2048
	ds_read_b128 v[116:119], v140 offset:0
	ds_read_b128 v[120:123], v140 offset:2048
	s_setprio 1
	v_mfma_f32_32x32x16_bf16 v[48:63], v[132:135], v[124:127], v[48:63]
	v_mfma_f32_32x32x16_bf16 v[32:47], v[132:135], v[128:131], v[32:47]
	v_mfma_f32_32x32x16_bf16 v[16:31], v[136:139], v[124:127], v[16:31]
	v_mfma_f32_32x32x16_bf16 v[0:15], v[136:139], v[128:131], v[0:15]
	s_setprio 0
	s_add_u32 m0, s64, 0x8000
	s_nop 0
	global_load_lds_dwordx4 v144, s[60:61]
	s_add_u32 m0, s64, 0xc000
	s_nop 0
	global_load_lds_dwordx4 v144, s[62:63]
	s_add_u32 m0, s64, 0x8400
	s_nop 0
	global_load_lds_dwordx4 v145, s[60:61]
	s_add_u32 m0, s64, 0xc400
	s_nop 0
	global_load_lds_dwordx4 v145, s[62:63]
	s_waitcnt lgkmcnt(0)
	s_setprio 1
	v_mfma_f32_32x32x16_bf16 v[48:63], v[116:119], v[108:111], v[48:63]
	v_mfma_f32_32x32x16_bf16 v[32:47], v[116:119], v[112:115], v[32:47]
	v_mfma_f32_32x32x16_bf16 v[16:31], v[120:123], v[108:111], v[16:31]
	v_mfma_f32_32x32x16_bf16 v[0:15], v[120:123], v[112:115], v[0:15]
	s_setprio 0
	ds_read_b128 v[124:127], v143 offset:0
	ds_read_b128 v[128:131], v143 offset:2048
	ds_read_b128 v[132:135], v141 offset:0
	ds_read_b128 v[136:139], v141 offset:2048
	v_xad_u32 v149, s70, v148, v146
	v_xad_u32 v150, s71, v148, v147
	s_add_u32 m0, s65, 0x8000
	s_nop 0
	global_load_lds_dwordx4 v149, s[94:95]
	s_add_u32 m0, s65, 0xbfc0
	s_nop 0
	global_load_lds_dwordx4 v149, s[94:95] offset:64
	s_add_u32 m0, s65, 0x8400
	s_nop 0
	global_load_lds_dwordx4 v150, s[94:95]
	s_add_u32 m0, s65, 0xc3c0
	s_nop 0
	global_load_lds_dwordx4 v150, s[94:95] offset:64
	s_add_u32 s70, s70, 0x80
	s_xor_b32 s71, s70, 0x800
	s_add_u32 s60, s60, 128
	s_addc_u32 s61, s61, 0
	s_add_u32 s62, s62, 128
	s_addc_u32 s63, s63, 0
	s_waitcnt lgkmcnt(0)
	s_barrier
	ds_read_b128 v[108:111], v142 offset:16384
	ds_read_b128 v[112:115], v142 offset:18432
	ds_read_b128 v[116:119], v140 offset:16384
	ds_read_b128 v[120:123], v140 offset:18432
	s_setprio 1
	v_mfma_f32_32x32x16_bf16 v[48:63], v[132:135], v[124:127], v[48:63]
	v_mfma_f32_32x32x16_bf16 v[32:47], v[132:135], v[128:131], v[32:47]
	v_mfma_f32_32x32x16_bf16 v[16:31], v[136:139], v[124:127], v[16:31]
	v_mfma_f32_32x32x16_bf16 v[0:15], v[136:139], v[128:131], v[0:15]
	s_setprio 0
	s_waitcnt lgkmcnt(0)
	s_setprio 1
	v_mfma_f32_32x32x16_bf16 v[48:63], v[116:119], v[108:111], v[48:63]
	v_mfma_f32_32x32x16_bf16 v[32:47], v[116:119], v[112:115], v[32:47]
	v_mfma_f32_32x32x16_bf16 v[16:31], v[120:123], v[108:111], v[16:31]
	v_mfma_f32_32x32x16_bf16 v[0:15], v[120:123], v[112:115], v[0:15]
	s_setprio 0
	ds_read_b128 v[124:127], v143 offset:16384
	ds_read_b128 v[128:131], v143 offset:18432
	ds_read_b128 v[132:135], v141 offset:16384
	ds_read_b128 v[136:139], v141 offset:18432
	s_waitcnt vmcnt(0) lgkmcnt(0)
	s_barrier
	ds_read_b128 v[108:111], v142 offset:32768
	ds_read_b128 v[112:115], v142 offset:34816
	ds_read_b128 v[116:119], v140 offset:32768
	ds_read_b128 v[120:123], v140 offset:34816
	s_setprio 1
	v_mfma_f32_32x32x16_bf16 v[48:63], v[132:135], v[124:127], v[48:63]
	v_mfma_f32_32x32x16_bf16 v[32:47], v[132:135], v[128:131], v[32:47]
	v_mfma_f32_32x32x16_bf16 v[16:31], v[136:139], v[124:127], v[16:31]
	v_mfma_f32_32x32x16_bf16 v[0:15], v[136:139], v[128:131], v[0:15]
	s_setprio 0
	s_waitcnt lgkmcnt(0)
	s_setprio 1
	v_mfma_f32_32x32x16_bf16 v[48:63], v[116:119], v[108:111], v[48:63]
	v_mfma_f32_32x32x16_bf16 v[32:47], v[116:119], v[112:115], v[32:47]
	v_mfma_f32_32x32x16_bf16 v[16:31], v[120:123], v[108:111], v[16:31]
	v_mfma_f32_32x32x16_bf16 v[0:15], v[120:123], v[112:115], v[0:15]
	s_setprio 0
	ds_read_b128 v[124:127], v143 offset:32768
	ds_read_b128 v[128:131], v143 offset:34816
	ds_read_b128 v[132:135], v141 offset:32768
	ds_read_b128 v[136:139], v141 offset:34816
	s_waitcnt lgkmcnt(0)
	s_barrier
	ds_read_b128 v[108:111], v142 offset:49152
	ds_read_b128 v[112:115], v142 offset:51200
	ds_read_b128 v[116:119], v140 offset:49152
	ds_read_b128 v[120:123], v140 offset:51200
	s_setprio 1
	v_mfma_f32_32x32x16_bf16 v[48:63], v[132:135], v[124:127], v[48:63]
	v_mfma_f32_32x32x16_bf16 v[32:47], v[132:135], v[128:131], v[32:47]
	v_mfma_f32_32x32x16_bf16 v[16:31], v[136:139], v[124:127], v[16:31]
	v_mfma_f32_32x32x16_bf16 v[0:15], v[136:139], v[128:131], v[0:15]
	s_setprio 0
	s_waitcnt lgkmcnt(0)
	s_setprio 1
	v_mfma_f32_32x32x16_bf16 v[48:63], v[116:119], v[108:111], v[48:63]
	v_mfma_f32_32x32x16_bf16 v[32:47], v[116:119], v[112:115], v[32:47]
	v_mfma_f32_32x32x16_bf16 v[16:31], v[120:123], v[108:111], v[16:31]
	v_mfma_f32_32x32x16_bf16 v[0:15], v[120:123], v[112:115], v[0:15]
	s_setprio 0
	ds_read_b128 v[124:127], v143 offset:49152
	ds_read_b128 v[128:131], v143 offset:51200
	ds_read_b128 v[132:135], v141 offset:49152
	ds_read_b128 v[136:139], v141 offset:51200
	s_waitcnt lgkmcnt(0)
	s_setprio 1
	v_mfma_f32_32x32x16_bf16 v[48:63], v[132:135], v[124:127], v[48:63]
	v_mfma_f32_32x32x16_bf16 v[32:47], v[132:135], v[128:131], v[32:47]
	v_mfma_f32_32x32x16_bf16 v[16:31], v[136:139], v[124:127], v[16:31]
	v_mfma_f32_32x32x16_bf16 v[0:15], v[136:139], v[128:131], v[0:15]
	s_setprio 0
